# ctx item tile loop: bias-load waits moved ahead of the exec-masked SUM store so they do not wait for its write
# baseline (speedup 1.0000x reference)
.LBB0_507:
	s_or_b32 s48, s48, s36
	s_lshl_b32 s34, s48, 4
	v_or_b32_e32 v54, s34, v109
	v_or_b32_e32 v0, s34, v108
	v_add_u32_e32 v6, v54, v79
	v_lshlrev_b32_e32 v148, 7, v0
	v_ashrrev_i32_e32 v7, 31, v6
	v_lshl_add_u64 v[4:5], v[62:63], 0, v[148:149]
	v_lshl_add_u64 v[6:7], v[6:7], 2, s[4:5]
	global_load_dwordx4 v[0:3], v[4:5], off
	global_load_dword v58, v[6:7], off
	v_add_u32_e32 v6, s37, v54
	v_ashrrev_i32_e32 v7, 31, v6
	v_lshl_add_u64 v[6:7], v[6:7], 2, s[4:5]
	global_load_dword v72, v[6:7], off
	v_lshl_add_u64 v[6:7], v[64:65], 0, v[148:149]
	global_load_dwordx4 v[80:83], v[6:7], off
	global_load_dwordx4 v[84:87], v[4:5], off offset:64
	global_load_dwordx4 v[116:119], v[6:7], off offset:64
	v_add_u32_e32 v24, s42, v54
	v_ashrrev_i32_e32 v25, 31, v24
	v_lshl_add_u64 v[24:25], v[24:25], 2, s[22:23]
	ds_read_b128 v[28:31], v115
	ds_read_b128 v[20:23], v115 offset:64
	ds_read_b128 v[16:19], v115 offset:4160
	ds_read_b128 v[12:15], v115 offset:4224
	ds_read_b128 v[8:11], v115 offset:8320
	ds_read_b128 v[4:7], v115 offset:8384
	v_lshl_add_u64 v[44:45], v[66:67], 0, v[148:149]
	global_load_dword v94, v[24:25], off
	s_nop 0
	global_load_dwordx4 v[24:27], v[44:45], off
	ds_read_b128 v[36:39], v115 offset:12480
	ds_read_b128 v[32:35], v115 offset:12544
	v_add_u32_e32 v52, s43, v54
	v_add_u32_e32 v56, s46, v54
	v_ashrrev_i32_e32 v53, 31, v52
	v_subrev_u32_e32 v92, s47, v52
	v_lshl_add_u32 v46, v54, 1, v110
	v_lshl_add_u64 v[76:77], v[68:69], 0, v[148:149]
	v_ashrrev_i32_e32 v57, 31, v56
	v_lshl_add_u64 v[52:53], v[52:53], 2, s[4:5]
	v_ashrrev_i32_e32 v93, 31, v92
	ds_read_u16 v55, v46
	ds_read_u16 v95, v46 offset:1040
	ds_read_u16 v102, v46 offset:2080
	ds_read_u16 v103, v46 offset:3120
	ds_read_u16 v106, v46 offset:4160
	ds_read_u16 v107, v46 offset:5200
	ds_read_u16 v144, v46 offset:6240
	ds_read_u16 v145, v46 offset:7280
	ds_read_u16 v147, v46 offset:8320
	ds_read_u16 v148, v46 offset:9360
	ds_read_u16 v154, v46 offset:10400
	ds_read_u16 v155, v46 offset:11440
	ds_read_u16 v156, v46 offset:12480
	ds_read_u16 v157, v46 offset:13520
	ds_read_u16 v158, v46 offset:14560
	ds_read_u16 v159, v46 offset:15600
	v_lshl_add_u64 v[100:101], v[56:57], 2, s[4:5]
	v_lshl_add_u64 v[92:93], v[92:93], 2, s[22:23]
	s_waitcnt lgkmcnt(14)
	v_lshlrev_b32_e32 v104, 16, v55
	v_lshlrev_b32_e32 v105, 16, v95
	s_waitcnt lgkmcnt(13)
	v_lshlrev_b32_e32 v102, 16, v102
	s_waitcnt lgkmcnt(12)
	v_lshlrev_b32_e32 v103, 16, v103
	v_ashrrev_i32_e32 v55, 31, v54
	s_waitcnt vmcnt(6)
	v_mov_b32_e32 v59, v58
	v_mov_b32_e32 v60, v58
	v_mov_b32_e32 v61, v58
	s_waitcnt vmcnt(5)
	v_mov_b32_e32 v73, v72
	v_mfma_f32_16x16x32_bf16 v[40:43], v[28:31], v[0:3], v[58:61]
	v_mov_b32_e32 v74, v72
	v_mov_b32_e32 v75, v72
	s_waitcnt vmcnt(3)
	v_mfma_f32_16x16x32_bf16 v[128:131], v[20:23], v[84:87], v[40:43]
	s_nop 3
	global_load_dwordx4 v[40:43], v[76:77], off
	s_nop 0
	global_load_dwordx4 v[44:47], v[44:45], off offset:64
	v_mfma_f32_16x16x32_bf16 v[48:51], v[28:31], v[80:83], v[72:75]
	v_mfma_f32_16x16x32_bf16 v[88:91], v[16:19], v[0:3], v[58:61]
	v_mfma_f32_16x16x32_bf16 v[120:123], v[8:11], v[0:3], v[58:61]
	s_waitcnt vmcnt(4)
	v_mfma_f32_16x16x32_bf16 v[132:135], v[20:23], v[116:119], v[48:51]
	s_nop 3
	global_load_dwordx4 v[48:51], v[76:77], off offset:64
	global_load_dword v56, v[52:53], off
	s_nop 0
	global_load_dword v52, v[100:101], off
	global_load_dword v78, v[92:93], off
	v_exp_f32_e32 v76, v128
	v_exp_f32_e32 v77, v129
	v_mfma_f32_16x16x32_bf16 v[0:3], v[36:39], v[0:3], v[58:61]
	s_waitcnt lgkmcnt(11)
	v_lshlrev_b32_e32 v100, 16, v106
	s_waitcnt lgkmcnt(10)
	v_lshlrev_b32_e32 v101, 16, v107
	s_waitcnt lgkmcnt(5)
	v_lshlrev_b32_e32 v92, 16, v154
	v_mfma_f32_16x16x32_bf16 v[96:99], v[16:19], v[80:83], v[72:75]
	s_waitcnt lgkmcnt(4)
	v_lshlrev_b32_e32 v93, 16, v155
	v_mfma_f32_16x16x32_bf16 v[124:127], v[8:11], v[80:83], v[72:75]
	v_mfma_f32_16x16x32_bf16 v[72:75], v[36:39], v[80:83], v[72:75]
	v_exp_f32_e32 v80, v130
	v_exp_f32_e32 v81, v131
	s_waitcnt lgkmcnt(1)
	v_lshlrev_b32_e32 v82, 16, v158
	v_mfma_f32_16x16x32_bf16 v[58:61], v[32:35], v[84:87], v[0:3]
	s_waitcnt lgkmcnt(0)
	v_lshlrev_b32_e32 v83, 16, v159
	v_pk_add_f32 v[80:81], v[80:81], 1.0 op_sel_hi:[1,0]
	v_pk_add_f32 v[0:1], v[76:77], 1.0 op_sel_hi:[1,0]
	v_rcp_f32_e32 v80, v80
	v_rcp_f32_e32 v76, v0
	v_rcp_f32_e32 v77, v1
	v_mfma_f32_16x16x32_bf16 v[0:3], v[32:35], v[116:119], v[72:75]
	v_rcp_f32_e32 v81, v81
	v_exp_f32_e32 v58, v58
	v_exp_f32_e32 v59, v59
	s_waitcnt vmcnt(7)
	v_pk_mul_f32 v[72:73], v[76:77], v[94:95] op_sel_hi:[1,0]
	v_mfma_f32_16x16x32_bf16 v[136:139], v[12:15], v[84:87], v[88:91]
	v_exp_f32_e32 v72, v72
	v_exp_f32_e32 v73, v73
	v_exp_f32_e32 v74, v132
	v_mfma_f32_16x16x32_bf16 v[140:143], v[12:15], v[116:119], v[96:99]
	v_exp_f32_e32 v75, v133
	v_pk_mul_f32 v[80:81], v[80:81], v[94:95] op_sel_hi:[1,0]
	v_pk_fma_f32 v[76:77], v[72:73], v[72:73], 1.0 op_sel_hi:[1,1,0] neg_lo:[1,0,0] neg_hi:[1,0,0] clamp
	v_exp_f32_e32 v106, v80
	v_exp_f32_e32 v107, v81
	v_exp_f32_e32 v80, v136
	v_exp_f32_e32 v81, v137
	v_mfma_f32_16x16x32_bf16 v[120:123], v[4:7], v[84:87], v[120:123]
	v_add_f32_e64 v74, v74, 1.0
	v_add_f32_e64 v75, v75, 1.0
	v_exp_f32_e32 v86, v140
	v_exp_f32_e32 v87, v141
	v_rcp_f32_e32 v74, v74
	v_rcp_f32_e32 v75, v75
	v_sqrt_f32_e32 v76, v76
	v_sqrt_f32_e32 v77, v77
	v_exp_f32_e32 v84, v134
	v_exp_f32_e32 v85, v135
	v_pk_add_f32 v[80:81], v[80:81], 1.0 op_sel_hi:[1,0]
	v_pk_add_f32 v[86:87], v[86:87], 1.0 op_sel_hi:[1,0]
	v_rcp_f32_e32 v80, v80
	v_rcp_f32_e32 v81, v81
	v_pk_mul_f32 v[74:75], v[74:75], v[104:105]
	v_rcp_f32_e32 v86, v86
	v_rcp_f32_e32 v87, v87
	v_pk_mul_f32 v[74:75], v[74:75], v[76:77]
	v_pk_add_f32 v[76:77], v[84:85], 1.0 op_sel_hi:[1,0]
	v_pk_fma_f32 v[84:85], v[106:107], v[106:107], 1.0 op_sel_hi:[1,1,0] neg_lo:[1,0,0] neg_hi:[1,0,0] clamp
	v_rcp_f32_e32 v76, v76
	v_rcp_f32_e32 v77, v77
	v_sqrt_f32_e32 v84, v84
	v_pk_mul_f32 v[80:81], v[80:81], v[94:95] op_sel_hi:[1,0]
	v_mfma_f32_16x16x32_bf16 v[124:127], v[4:7], v[116:119], v[124:127]
	v_sqrt_f32_e32 v85, v85
	v_exp_f32_e32 v118, v80
	v_exp_f32_e32 v119, v81
	v_pk_mul_f32 v[80:81], v[86:87], v[100:101]
	v_exp_f32_e32 v86, v138
	v_exp_f32_e32 v87, v139
	v_pk_mul_f32 v[76:77], v[76:77], v[102:103]
	v_exp_f32_e32 v88, v120
	v_pk_mul_f32 v[76:77], v[76:77], v[84:85]
	v_pk_fma_f32 v[84:85], v[118:119], v[118:119], 1.0 op_sel_hi:[1,1,0] neg_lo:[1,0,0] neg_hi:[1,0,0] clamp
	v_pk_add_f32 v[86:87], v[86:87], 1.0 op_sel_hi:[1,0]
	v_exp_f32_e32 v89, v121
	v_rcp_f32_e32 v86, v86
	v_rcp_f32_e32 v87, v87
	v_sqrt_f32_e32 v84, v84
	v_sqrt_f32_e32 v85, v85
	v_pk_add_f32 v[88:89], v[88:89], 1.0 op_sel_hi:[1,0]
	v_pk_mul_f32 v[86:87], v[86:87], v[94:95] op_sel_hi:[1,0]
	v_rcp_f32_e32 v88, v88
	v_rcp_f32_e32 v89, v89
	v_exp_f32_e32 v128, v86
	v_exp_f32_e32 v129, v87
	v_pk_mul_f32 v[80:81], v[80:81], v[84:85]
	v_exp_f32_e32 v84, v142
	v_exp_f32_e32 v85, v143
	v_pk_mul_f32 v[88:89], v[94:95], v[88:89] op_sel_hi:[0,1]
	v_pk_fma_f32 v[86:87], v[128:129], v[128:129], 1.0 op_sel_hi:[1,1,0] neg_lo:[1,0,0] neg_hi:[1,0,0] clamp
	v_exp_f32_e32 v120, v88
	v_exp_f32_e32 v121, v89
	v_exp_f32_e32 v88, v122
	v_exp_f32_e32 v89, v123
	v_pk_add_f32 v[84:85], v[84:85], 1.0 op_sel_hi:[1,0]
	v_rcp_f32_e32 v84, v84
	v_rcp_f32_e32 v85, v85
	v_sqrt_f32_e32 v86, v86
	v_sqrt_f32_e32 v87, v87
	v_exp_f32_e32 v116, v124
	v_exp_f32_e32 v117, v125
	v_pk_add_f32 v[88:89], v[88:89], 1.0 op_sel_hi:[1,0]
	v_lshlrev_b32_e32 v98, 16, v144
	v_lshlrev_b32_e32 v99, 16, v145
	v_rcp_f32_e32 v88, v88
	v_rcp_f32_e32 v89, v89
	v_pk_mul_f32 v[84:85], v[84:85], v[98:99]
	v_exp_f32_e32 v122, v126
	v_pk_mul_f32 v[84:85], v[84:85], v[86:87]
	v_pk_add_f32 v[86:87], v[116:117], 1.0 op_sel_hi:[1,0]
	v_pk_fma_f32 v[116:117], v[120:121], v[120:121], 1.0 op_sel_hi:[1,1,0] neg_lo:[1,0,0] neg_hi:[1,0,0] clamp
	v_rcp_f32_e32 v86, v86
	v_rcp_f32_e32 v87, v87
	v_sqrt_f32_e32 v116, v116
	v_pk_mul_f32 v[88:89], v[94:95], v[88:89] op_sel_hi:[0,1]
	v_sqrt_f32_e32 v117, v117
	v_exp_f32_e32 v124, v88
	v_exp_f32_e32 v125, v89
	v_exp_f32_e32 v123, v127
	v_pk_add_f32 v[58:59], v[58:59], 1.0 op_sel_hi:[1,0]
	v_lshlrev_b32_e32 v96, 16, v147
	v_lshlrev_b32_e32 v97, 16, v148
	v_rcp_f32_e32 v58, v58
	v_rcp_f32_e32 v59, v59
	v_exp_f32_e32 v60, v60
	v_exp_f32_e32 v61, v61
	v_pk_mul_f32 v[86:87], v[86:87], v[96:97]
	v_pk_add_f32 v[122:123], v[122:123], 1.0 op_sel_hi:[1,0]
	v_pk_mul_f32 v[86:87], v[86:87], v[116:117]
	v_pk_fma_f32 v[116:117], v[124:125], v[124:125], 1.0 op_sel_hi:[1,1,0] neg_lo:[1,0,0] neg_hi:[1,0,0] clamp
	v_rcp_f32_e32 v122, v122
	v_rcp_f32_e32 v123, v123
	v_sqrt_f32_e32 v116, v116
	v_pk_mul_f32 v[58:59], v[94:95], v[58:59] op_sel_hi:[0,1]
	v_pk_add_f32 v[60:61], v[60:61], 1.0 op_sel_hi:[1,0]
	v_sqrt_f32_e32 v117, v117
	v_exp_f32_e32 v58, v58
	v_exp_f32_e32 v59, v59
	v_rcp_f32_e32 v60, v60
	v_rcp_f32_e32 v61, v61
	v_exp_f32_e32 v0, v0
	v_exp_f32_e32 v1, v1
	v_pk_mul_f32 v[88:89], v[122:123], v[92:93]
	v_pk_mul_f32 v[60:61], v[94:95], v[60:61] op_sel_hi:[0,1]
	v_pk_mul_f32 v[88:89], v[88:89], v[116:117]
	v_pk_fma_f32 v[116:117], v[58:59], v[58:59], 1.0 op_sel_hi:[1,1,0] neg_lo:[1,0,0] neg_hi:[1,0,0] clamp
	v_pk_add_f32 v[0:1], v[0:1], 1.0 op_sel_hi:[1,0]
	v_exp_f32_e32 v94, v60
	v_exp_f32_e32 v95, v61
	v_rcp_f32_e32 v0, v0
	v_rcp_f32_e32 v1, v1
	v_sqrt_f32_e32 v116, v116
	v_exp_f32_e32 v2, v2
	v_exp_f32_e32 v3, v3
	v_sqrt_f32_e32 v117, v117
	v_lshlrev_b32_e32 v90, 16, v156
	v_lshlrev_b32_e32 v91, 16, v157
	v_pk_fma_f32 v[60:61], v[94:95], v[94:95], 1.0 op_sel_hi:[1,1,0] neg_lo:[1,0,0] neg_hi:[1,0,0] clamp
	v_fma_f32 v74, 0, v72, v74
	v_pk_add_f32 v[2:3], v[2:3], 1.0 op_sel_hi:[1,0]
	v_pk_mul_f32 v[0:1], v[0:1], v[90:91]
	v_fmac_f32_e32 v75, v73, v74
	v_mul_f32_e32 v73, v72, v73
	v_rcp_f32_e32 v2, v2
	v_rcp_f32_e32 v3, v3
	v_sqrt_f32_e32 v122, v60
	v_max_f32_e32 v53, 0, v61
	v_pk_mul_f32 v[60:61], v[0:1], v[116:117]
	v_mul_f32_e32 v116, v106, v73
	v_fma_f32 v76, v106, v75, v76
	v_sqrt_f32_e32 v123, v53
	v_fmac_f32_e32 v77, v107, v76
	v_mul_f32_e32 v106, v107, v116
	v_mul_f32_e32 v107, v118, v106
	v_fma_f32 v80, v118, v77, v80
	v_fmac_f32_e32 v81, v119, v80
	v_mul_f32_e32 v118, v119, v107
	v_pk_mul_f32 v[0:1], v[2:3], v[82:83]
	v_mul_f32_e32 v119, v128, v118
	v_fma_f32 v84, v128, v81, v84
	v_pk_mul_f32 v[0:1], v[0:1], v[122:123]
	v_fmac_f32_e32 v85, v129, v84
	v_mul_f32_e32 v122, v129, v119
	v_mul_f32_e32 v117, v120, v122
	v_fma_f32 v86, v120, v85, v86
	v_fmac_f32_e32 v87, v121, v86
	v_mul_f32_e32 v120, v121, v117
	v_mul_f32_e32 v121, v124, v120
	v_fma_f32 v88, v124, v87, v88
	v_fmac_f32_e32 v89, v125, v88
	v_mul_f32_e32 v123, v125, v121
	v_mul_f32_e32 v124, v58, v123
	v_fma_f32 v60, v58, v89, v60
	v_fmac_f32_e32 v61, v59, v60
	v_mul_f32_e32 v125, v59, v124
	v_mul_f32_e32 v126, v94, v125
	v_fma_f32 v0, v94, v61, v0
	v_fmac_f32_e32 v1, v95, v0
	v_mul_f32_e32 v2, v95, v126
	ds_bpermute_b32 v127, v111, v2
	ds_bpermute_b32 v3, v111, v1
	ds_bpermute_b32 v128, v112, v2
	ds_bpermute_b32 v53, v112, v1
	ds_bpermute_b32 v129, v113, v2
	ds_bpermute_b32 v57, v113, v1
	ds_bpermute_b32 v130, v114, v2
	ds_bpermute_b32 v59, v114, v1
	v_lshl_add_u64 v[94:95], v[54:55], 3, s[24:25]
	s_waitcnt vmcnt(0)
	s_and_saveexec_b64 s[34:35], s[40:41]
	s_cbranch_execz .LBB0_509
	s_waitcnt lgkmcnt(6)
	v_fmac_f32_e32 v3, 0, v127
	s_waitcnt lgkmcnt(5)
	v_mul_f32_e32 v54, v127, v128
	s_waitcnt lgkmcnt(4)
	v_fmac_f32_e32 v53, v3, v128
	s_waitcnt lgkmcnt(3)
	v_mul_f32_e32 v54, v54, v129
	s_waitcnt lgkmcnt(2)
	v_fmac_f32_e32 v57, v53, v129
	s_waitcnt lgkmcnt(1)
	v_mul_f32_e32 v58, v54, v130
	s_waitcnt lgkmcnt(0)
	v_fmac_f32_e32 v59, v57, v130
	global_store_dwordx2 v[94:95], v[58:59], off sc1
.LBB0_509:
	s_or_b64 exec, exec, s[34:35]
	s_waitcnt lgkmcnt(2)
	v_mov_b32_e32 v57, v56
	v_mov_b32_e32 v58, v56
	s_waitcnt lgkmcnt(0)
	v_mov_b32_e32 v59, v56
	s_nop 0
	v_mov_b32_e32 v53, v52
	v_mov_b32_e32 v54, v52
	v_mov_b32_e32 v55, v52
	v_mfma_f32_16x16x32_bf16 v[128:131], v[28:31], v[24:27], v[56:59]
	s_nop 0
	v_mfma_f32_16x16x32_bf16 v[28:31], v[28:31], v[40:43], v[52:55]
	v_mfma_f32_16x16x32_bf16 v[128:131], v[20:23], v[44:47], v[128:131]
	v_mfma_f32_16x16x32_bf16 v[132:135], v[20:23], v[48:51], v[28:31]
	v_mfma_f32_16x16x32_bf16 v[20:23], v[16:19], v[24:27], v[56:59]
	v_mfma_f32_16x16x32_bf16 v[16:19], v[16:19], v[40:43], v[52:55]
	v_mfma_f32_16x16x32_bf16 v[28:31], v[12:15], v[44:47], v[20:23]
	v_mfma_f32_16x16x32_bf16 v[20:23], v[12:15], v[48:51], v[16:19]
	v_mfma_f32_16x16x32_bf16 v[12:15], v[8:11], v[24:27], v[56:59]
	s_nop 5
	v_exp_f32_e32 v28, v28
	v_exp_f32_e32 v29, v29
	v_exp_f32_e32 v30, v30
	v_mfma_f32_16x16x32_bf16 v[8:11], v[8:11], v[40:43], v[52:55]
	v_exp_f32_e32 v31, v31
	v_pk_add_f32 v[28:29], v[28:29], 1.0 op_sel_hi:[1,0]
	v_exp_f32_e32 v20, v20
	v_mfma_f32_16x16x32_bf16 v[16:19], v[4:7], v[44:47], v[12:15]
	v_rcp_f32_e32 v28, v28
	v_rcp_f32_e32 v29, v29
	v_exp_f32_e32 v21, v21
	v_mfma_f32_16x16x32_bf16 v[12:15], v[4:7], v[48:51], v[8:11]
	v_add_f32_e64 v30, v30, 1.0
	v_add_f32_e64 v31, v31, 1.0
	s_nop 0
	v_pk_mul_f32 v[28:29], v[28:29], v[78:79] op_sel_hi:[1,0]
	v_rcp_f32_e32 v30, v30
	v_mfma_f32_16x16x32_bf16 v[4:7], v[36:39], v[24:27], v[56:59]
	v_exp_f32_e32 v28, v28
	v_exp_f32_e32 v29, v29
	v_rcp_f32_e32 v31, v31
	v_mfma_f32_16x16x32_bf16 v[24:27], v[36:39], v[40:43], v[52:55]
	v_exp_f32_e32 v16, v16
	v_exp_f32_e32 v17, v17
	v_pk_add_f32 v[20:21], v[20:21], 1.0 op_sel_hi:[1,0]
	v_mfma_f32_16x16x32_bf16 v[8:11], v[32:35], v[44:47], v[4:7]
	v_rcp_f32_e32 v20, v20
	v_rcp_f32_e32 v21, v21
	v_pk_mul_f32 v[30:31], v[30:31], v[78:79] op_sel_hi:[1,0]
	v_mfma_f32_16x16x32_bf16 v[4:7], v[32:35], v[48:51], v[24:27]
	v_exp_f32_e32 v34, v134
	v_exp_f32_e32 v35, v135
	v_exp_f32_e32 v30, v30
	v_exp_f32_e32 v24, v128
	v_exp_f32_e32 v25, v129
	v_exp_f32_e32 v26, v132
	v_exp_f32_e32 v27, v133
	v_pk_add_f32 v[34:35], v[34:35], 1.0 op_sel_hi:[1,0]
	v_pk_add_f32 v[24:25], v[24:25], 1.0 op_sel_hi:[1,0]
	v_rcp_f32_e32 v34, v34
	v_pk_add_f32 v[26:27], v[26:27], 1.0 op_sel_hi:[1,0]
	v_rcp_f32_e32 v24, v24
	v_rcp_f32_e32 v25, v25
	v_rcp_f32_e32 v26, v26
	v_rcp_f32_e32 v27, v27
	v_rcp_f32_e32 v35, v35
	v_pk_mul_f32 v[24:25], v[24:25], v[78:79] op_sel_hi:[1,0]
	v_exp_f32_e32 v31, v31
	v_pk_mul_f32 v[32:33], v[26:27], v[104:105]
	v_exp_f32_e32 v26, v24
	v_exp_f32_e32 v27, v25
	v_pk_mul_f32 v[36:37], v[34:35], v[102:103]
	v_exp_f32_e32 v22, v22
	v_exp_f32_e32 v23, v23
	v_pk_fma_f32 v[24:25], v[26:27], v[26:27], 1.0 op_sel_hi:[1,1,0] neg_lo:[1,0,0] neg_hi:[1,0,0] clamp
	v_pk_add_f32 v[16:17], v[16:17], 1.0 op_sel_hi:[1,0]
	v_sqrt_f32_e32 v24, v24
	v_sqrt_f32_e32 v25, v25
	v_rcp_f32_e32 v16, v16
	v_rcp_f32_e32 v17, v17
	v_pk_mul_f32 v[20:21], v[20:21], v[100:101]
	v_pk_mul_f32 v[24:25], v[32:33], v[24:25]
	v_exp_f32_e32 v32, v130
	v_exp_f32_e32 v33, v131
	v_exp_f32_e32 v18, v18
	v_exp_f32_e32 v19, v19
	v_pk_add_f32 v[22:23], v[22:23], 1.0 op_sel_hi:[1,0]
	v_pk_add_f32 v[32:33], v[32:33], 1.0 op_sel_hi:[1,0]
	v_rcp_f32_e32 v22, v22
	v_rcp_f32_e32 v32, v32
	v_rcp_f32_e32 v33, v33
	v_rcp_f32_e32 v23, v23
	v_pk_mul_f32 v[16:17], v[78:79], v[16:17] op_sel_hi:[0,1]
	v_exp_f32_e32 v8, v8
	v_pk_mul_f32 v[32:33], v[32:33], v[78:79] op_sel_hi:[1,0]
	v_exp_f32_e32 v9, v9
	v_exp_f32_e32 v34, v32
	v_exp_f32_e32 v35, v33
	v_exp_f32_e32 v16, v16
	v_exp_f32_e32 v17, v17
	v_exp_f32_e32 v12, v12
	v_pk_fma_f32 v[32:33], v[34:35], v[34:35], 1.0 op_sel_hi:[1,1,0] neg_lo:[1,0,0] neg_hi:[1,0,0] clamp
	v_exp_f32_e32 v13, v13
	v_sqrt_f32_e32 v32, v32
	v_sqrt_f32_e32 v33, v33
	v_pk_add_f32 v[18:19], v[18:19], 1.0 op_sel_hi:[1,0]
	v_pk_mul_f32 v[22:23], v[22:23], v[98:99]
	v_rcp_f32_e32 v18, v18
	v_pk_mul_f32 v[32:33], v[36:37], v[32:33]
	v_pk_fma_f32 v[36:37], v[28:29], v[28:29], 1.0 op_sel_hi:[1,1,0] neg_lo:[1,0,0] neg_hi:[1,0,0] clamp
	v_rcp_f32_e32 v19, v19
	v_sqrt_f32_e32 v36, v36
	v_sqrt_f32_e32 v37, v37
	v_pk_add_f32 v[8:9], v[8:9], 1.0 op_sel_hi:[1,0]
	v_pk_add_f32 v[12:13], v[12:13], 1.0 op_sel_hi:[1,0]
	v_rcp_f32_e32 v8, v8
	v_pk_mul_f32 v[20:21], v[20:21], v[36:37]
	v_pk_fma_f32 v[36:37], v[30:31], v[30:31], 1.0 op_sel_hi:[1,1,0] neg_lo:[1,0,0] neg_hi:[1,0,0] clamp
	v_rcp_f32_e32 v9, v9
	v_sqrt_f32_e32 v36, v36
	v_sqrt_f32_e32 v37, v37
	v_rcp_f32_e32 v12, v12
	v_rcp_f32_e32 v13, v13
	v_pk_mul_f32 v[18:19], v[78:79], v[18:19] op_sel_hi:[0,1]
	v_pk_mul_f32 v[22:23], v[22:23], v[36:37]
	v_pk_fma_f32 v[36:37], v[16:17], v[16:17], 1.0 op_sel_hi:[1,1,0] neg_lo:[1,0,0] neg_hi:[1,0,0] clamp
	v_exp_f32_e32 v18, v18
	v_sqrt_f32_e32 v36, v36
	v_sqrt_f32_e32 v37, v37
	v_exp_f32_e32 v19, v19
	v_pk_mul_f32 v[8:9], v[78:79], v[8:9] op_sel_hi:[0,1]
	v_exp_f32_e32 v38, v8
	v_exp_f32_e32 v39, v9
	v_pk_mul_f32 v[12:13], v[12:13], v[96:97]
	v_exp_f32_e32 v4, v4
	v_exp_f32_e32 v5, v5
	v_pk_mul_f32 v[12:13], v[12:13], v[36:37]
	v_pk_fma_f32 v[36:37], v[18:19], v[18:19], 1.0 op_sel_hi:[1,1,0] neg_lo:[1,0,0] neg_hi:[1,0,0] clamp
	v_pk_fma_f32 v[8:9], v[38:39], v[38:39], 1.0 op_sel_hi:[1,1,0] neg_lo:[1,0,0] neg_hi:[1,0,0] clamp
	v_sqrt_f32_e32 v36, v36
	v_sqrt_f32_e32 v37, v37
	v_pk_add_f32 v[4:5], v[4:5], 1.0 op_sel_hi:[1,0]
	v_rcp_f32_e32 v4, v4
	v_rcp_f32_e32 v5, v5
	v_sqrt_f32_e32 v8, v8
	v_sqrt_f32_e32 v9, v9
	v_pk_mul_f32 v[4:5], v[4:5], v[90:91]
	v_exp_f32_e32 v6, v6
	v_exp_f32_e32 v7, v7
	v_pk_mul_f32 v[4:5], v[4:5], v[8:9]
	v_exp_f32_e32 v8, v10
	v_exp_f32_e32 v9, v11
	v_pk_add_f32 v[6:7], v[6:7], 1.0 op_sel_hi:[1,0]
	v_exp_f32_e32 v14, v14
	v_rcp_f32_e32 v6, v6
	v_pk_add_f32 v[8:9], v[8:9], 1.0 op_sel_hi:[1,0]
	v_rcp_f32_e32 v7, v7
	v_rcp_f32_e32 v8, v8
	v_rcp_f32_e32 v9, v9
	v_exp_f32_e32 v15, v15
	v_pk_mul_f32 v[10:11], v[6:7], v[82:83]
	v_pk_mul_f32 v[8:9], v[78:79], v[8:9] op_sel_hi:[0,1]
	v_exp_f32_e32 v6, v8
	v_exp_f32_e32 v7, v9
	v_pk_add_f32 v[14:15], v[14:15], 1.0 op_sel_hi:[1,0]
	v_pk_fma_f32 v[8:9], v[6:7], v[6:7], 1.0 op_sel_hi:[1,1,0] neg_lo:[1,0,0] neg_hi:[1,0,0] clamp
	s_nop 0
	v_sqrt_f32_e32 v8, v8
	v_sqrt_f32_e32 v9, v9
	v_rcp_f32_e32 v14, v14
	v_rcp_f32_e32 v15, v15
	v_pk_mul_f32 v[8:9], v[10:11], v[8:9]
	s_nop 0
	v_fma_f32 v9, 0, v7, v9
	v_pk_mul_f32 v[14:15], v[14:15], v[92:93]
	v_fmac_f32_e32 v8, v6, v9
	v_mul_f32_e32 v6, v7, v6
	v_pk_mul_f32 v[14:15], v[14:15], v[36:37]
	v_mul_f32_e32 v36, v39, v6
	v_fma_f32 v5, v39, v8, v5
	v_fmac_f32_e32 v4, v38, v5
	v_mul_f32_e32 v37, v38, v36
	v_mul_f32_e32 v38, v19, v37
	v_fma_f32 v15, v19, v4, v15
	v_fmac_f32_e32 v14, v18, v15
	v_mul_f32_e32 v18, v18, v38
	v_mul_f32_e32 v19, v17, v18
	v_fma_f32 v13, v17, v14, v13
	v_fmac_f32_e32 v12, v16, v13
	v_mul_f32_e32 v16, v16, v19
	v_mul_f32_e32 v17, v31, v16
	v_fma_f32 v23, v31, v12, v23
	v_fmac_f32_e32 v22, v30, v23
	v_mul_f32_e32 v30, v30, v17
	v_mul_f32_e32 v31, v29, v30
	v_fma_f32 v21, v29, v22, v21
	v_fmac_f32_e32 v20, v28, v21
	v_mul_f32_e32 v28, v28, v31
	v_mul_f32_e32 v29, v35, v28
	v_fma_f32 v33, v35, v20, v33
	v_fmac_f32_e32 v32, v34, v33
	v_mul_f32_e32 v34, v34, v29
	v_mul_f32_e32 v35, v27, v34
	v_fma_f32 v25, v27, v32, v25
	v_fmac_f32_e32 v24, v26, v25
	v_mul_f32_e32 v3, v26, v35
	ds_bpermute_b32 v40, v114, v3
	ds_bpermute_b32 v26, v114, v24
	ds_bpermute_b32 v41, v113, v3
	ds_bpermute_b32 v27, v113, v24
	ds_bpermute_b32 v42, v112, v3
	ds_bpermute_b32 v39, v112, v24
	ds_bpermute_b32 v43, v111, v3
	ds_bpermute_b32 v11, v111, v24
	s_and_saveexec_b64 s[34:35], s[40:41]
	s_cbranch_execz .LBB0_506
	s_waitcnt lgkmcnt(6)
	v_fmac_f32_e32 v26, 0, v40
	s_waitcnt lgkmcnt(5)
	v_mul_f32_e32 v10, v40, v41
	s_waitcnt lgkmcnt(4)
	v_fmac_f32_e32 v27, v26, v41
	s_waitcnt lgkmcnt(3)
	v_mul_f32_e32 v10, v10, v42
	s_waitcnt lgkmcnt(2)
	v_fmac_f32_e32 v39, v27, v42
	v_add_co_u32_e32 v26, vcc, 0x1000, v94
	s_waitcnt lgkmcnt(1)
	v_mul_f32_e32 v10, v10, v43
	s_waitcnt lgkmcnt(0)
	v_fmac_f32_e32 v11, v39, v43
	v_addc_co_u32_e32 v27, vcc, 0, v95, vcc
	global_store_dwordx2 v[26:27], v[10:11], off sc1
	s_branch .LBB0_506
